# half-tile balancing for the 4.5-round bf16-output GEMM phases via a separate half-tile K-loop copy
# baseline (speedup 1.0000x reference)
.Lhalf_A:
	s_add_i32 s49, s42, 2
	s_add_u32 vcc_lo, s0, 0x80
	s_addc_u32 s43, s1, 0
	s_add_i32 s10, 0, 0x10000
	s_cmp_eq_u32 s47, s42
	s_cselect_b32 s43, s35, s43
	s_cselect_b32 s42, s34, vcc_lo
	s_cselect_b32 vcc_hi, s29, s45
	s_cselect_b32 vcc_lo, s28, s44
	s_add_i32 s52, 0, 0x14000
	v_add_u32_e32 v86, s10, v172
	v_add_u32_e32 v175, s52, v172
	ds_read_b128 v[66:69], v86
	ds_read_b128 v[70:73], v86 offset:1024
	ds_read_b128 v[82:85], v86 offset:2048
	ds_read_b128 v[86:89], v86 offset:3072
	ds_read_b128 v[146:149], v175
	ds_read_b128 v[162:165], v175 offset:1024
	ds_read_b128 v[168:171], v175 offset:2048
	ds_read_b128 v[176:179], v175 offset:3072
	v_lshl_add_u64 v[188:189], s[0:1], 0, v[158:159]
	s_add_i32 m0, s7, 0xc000
	ds_read_b128 v[180:183], v174
	ds_read_b128 v[184:187], v174 offset:1024
	ds_read_b128 v[216:219], v174 offset:2048
	ds_read_b128 v[224:227], v174 offset:3072
	ds_read_b128 v[228:231], v174 offset:4096
	ds_read_b128 v[232:235], v174 offset:5120
	ds_read_b128 v[236:239], v174 offset:6144
	ds_read_b128 v[240:243], v174 offset:7168
	global_load_lds_dwordx4 v[188:189], off
	v_lshl_add_u64 v[188:189], s[0:1], 0, v[160:161]
	s_add_i32 m0, s7, 0xe000
	s_nop 0
	global_load_lds_dwordx4 v[188:189], off
	s_waitcnt vmcnt(8)
	s_waitcnt lgkmcnt(0)
	s_barrier
	s_setprio 1
	s_waitcnt lgkmcnt(0)
	v_mfma_f32_16x16x32_bf16 v[138:141], v[66:69], v[180:183], v[138:141]
	v_mfma_f32_16x16x32_bf16 v[142:145], v[82:85], v[180:183], v[142:145]
	v_mfma_f32_16x16x32_bf16 v[126:129], v[66:69], v[216:219], v[126:129]
	v_mfma_f32_16x16x32_bf16 v[122:125], v[82:85], v[216:219], v[122:125]
	v_mfma_f32_16x16x32_bf16 v[110:113], v[66:69], v[228:231], v[110:113]
	v_mfma_f32_16x16x32_bf16 v[106:109], v[82:85], v[228:231], v[106:109]
	v_mfma_f32_16x16x32_bf16 v[94:97], v[66:69], v[236:239], v[94:97]
	v_mfma_f32_16x16x32_bf16 v[90:93], v[82:85], v[236:239], v[90:93]
	v_mfma_f32_16x16x32_bf16 v[138:141], v[70:73], v[184:187], v[138:141]
	v_mfma_f32_16x16x32_bf16 v[142:145], v[86:89], v[184:187], v[142:145]
	v_mfma_f32_16x16x32_bf16 v[126:129], v[70:73], v[224:227], v[126:129]
	v_mfma_f32_16x16x32_bf16 v[122:125], v[86:89], v[224:227], v[122:125]
	v_mfma_f32_16x16x32_bf16 v[110:113], v[70:73], v[232:235], v[110:113]
	v_mfma_f32_16x16x32_bf16 v[106:109], v[86:89], v[232:235], v[106:109]
	v_mfma_f32_16x16x32_bf16 v[94:97], v[70:73], v[240:243], v[94:97]
	v_mfma_f32_16x16x32_bf16 v[90:93], v[86:89], v[240:243], v[90:93]
	s_setprio 0
	s_setprio 1
	v_mfma_f32_16x16x32_bf16 v[134:137], v[146:149], v[180:183], v[134:137]
	v_mfma_f32_16x16x32_bf16 v[130:133], v[168:171], v[180:183], v[130:133]
	v_mfma_f32_16x16x32_bf16 v[118:121], v[146:149], v[216:219], v[118:121]
	v_mfma_f32_16x16x32_bf16 v[114:117], v[168:171], v[216:219], v[114:117]
	v_mfma_f32_16x16x32_bf16 v[102:105], v[146:149], v[228:231], v[102:105]
	v_mfma_f32_16x16x32_bf16 v[98:101], v[168:171], v[228:231], v[98:101]
	v_mfma_f32_16x16x32_bf16 v[78:81], v[146:149], v[236:239], v[78:81]
	v_mfma_f32_16x16x32_bf16 v[74:77], v[168:171], v[236:239], v[74:77]
	v_mfma_f32_16x16x32_bf16 v[134:137], v[162:165], v[184:187], v[134:137]
	v_mfma_f32_16x16x32_bf16 v[130:133], v[176:179], v[184:187], v[130:133]
	v_mfma_f32_16x16x32_bf16 v[118:121], v[162:165], v[224:227], v[118:121]
	v_mfma_f32_16x16x32_bf16 v[114:117], v[176:179], v[224:227], v[114:117]
	v_mfma_f32_16x16x32_bf16 v[102:105], v[162:165], v[232:235], v[102:105]
	v_mfma_f32_16x16x32_bf16 v[98:101], v[176:179], v[232:235], v[98:101]
	v_mfma_f32_16x16x32_bf16 v[78:81], v[162:165], v[240:243], v[78:81]
	v_mfma_f32_16x16x32_bf16 v[74:77], v[176:179], v[240:243], v[74:77]
	s_setprio 0
	s_barrier
	s_add_i32 s10, s10, s94
	v_lshl_add_u64 v[188:189], vcc, 0, v[32:33]
	s_mov_b32 m0, s10
	global_load_lds_dwordx4 v[188:189], off
	s_add_i32 m0, s10, 0x2000
	v_lshl_add_u64 v[244:245], vcc, 0, v[154:155]
	s_add_u32 vcc_lo, vcc_lo, s96
	s_addc_u32 vcc_hi, vcc_hi, s97
	s_add_i32 s10, s52, s94
	global_load_lds_dwordx4 v[244:245], off
	v_lshl_add_u64 v[246:247], vcc, 0, v[32:33]
	s_mov_b32 m0, s10
	v_lshl_add_u64 v[248:249], vcc, 0, v[154:155]
	global_load_lds_dwordx4 v[246:247], off
	s_add_i32 m0, s10, 0x2000
	v_lshl_add_u64 v[202:203], s[42:43], 0, v[150:151]
	global_load_lds_dwordx4 v[248:249], off
	s_mov_b32 m0, s7
	v_lshl_add_u64 v[212:213], s[42:43], 0, v[152:153]
	global_load_lds_dwordx4 v[202:203], off
	s_mov_b32 m0, s2
	s_nop 0
	global_load_lds_dwordx4 v[212:213], off
	s_waitcnt vmcnt(8)
	s_waitcnt lgkmcnt(0)
	s_barrier
	s_setprio 1
	s_waitcnt lgkmcnt(0)
	s_setprio 0
	s_setprio 1
	s_setprio 0
	s_barrier
	s_add_i32 s10, 0, 0x18000
	s_add_i32 s52, 0, 0x1c000
	v_add_u32_e32 v86, s10, v172
	v_add_u32_e32 v175, s52, v172
	ds_read_b128 v[66:69], v86
	ds_read_b128 v[70:73], v86 offset:1024
	ds_read_b128 v[82:85], v86 offset:2048
	ds_read_b128 v[86:89], v86 offset:3072
	ds_read_b128 v[146:149], v175
	ds_read_b128 v[162:165], v175 offset:1024
	ds_read_b128 v[168:171], v175 offset:2048
	ds_read_b128 v[176:179], v175 offset:3072
	s_add_u32 s42, s42, s96
	s_addc_u32 s43, s43, s97
	s_mov_b32 m0, s3
	v_lshl_add_u64 v[204:205], s[42:43], 0, v[150:151]
	ds_read_b128 v[180:183], v174 offset:32768
	ds_read_b128 v[184:187], v174 offset:33792
	ds_read_b128 v[216:219], v174 offset:34816
	ds_read_b128 v[224:227], v174 offset:35840
	ds_read_b128 v[228:231], v174 offset:36864
	ds_read_b128 v[232:235], v174 offset:37888
	ds_read_b128 v[236:239], v174 offset:38912
	ds_read_b128 v[240:243], v174 offset:39936
	global_load_lds_dwordx4 v[204:205], off
	v_lshl_add_u64 v[204:205], s[42:43], 0, v[152:153]
	s_mov_b32 m0, s17
	s_nop 0
	global_load_lds_dwordx4 v[204:205], off
	s_waitcnt vmcnt(8)
	s_waitcnt lgkmcnt(0)
	s_barrier
	s_setprio 1
	s_waitcnt lgkmcnt(0)
	v_mfma_f32_16x16x32_bf16 v[138:141], v[66:69], v[180:183], v[138:141]
	v_mfma_f32_16x16x32_bf16 v[142:145], v[82:85], v[180:183], v[142:145]
	v_mfma_f32_16x16x32_bf16 v[126:129], v[66:69], v[216:219], v[126:129]
	v_mfma_f32_16x16x32_bf16 v[122:125], v[82:85], v[216:219], v[122:125]
	v_mfma_f32_16x16x32_bf16 v[110:113], v[66:69], v[228:231], v[110:113]
	v_mfma_f32_16x16x32_bf16 v[106:109], v[82:85], v[228:231], v[106:109]
	v_mfma_f32_16x16x32_bf16 v[94:97], v[66:69], v[236:239], v[94:97]
	v_mfma_f32_16x16x32_bf16 v[90:93], v[82:85], v[236:239], v[90:93]
	v_mfma_f32_16x16x32_bf16 v[138:141], v[70:73], v[184:187], v[138:141]
	v_mfma_f32_16x16x32_bf16 v[142:145], v[86:89], v[184:187], v[142:145]
	v_mfma_f32_16x16x32_bf16 v[126:129], v[70:73], v[224:227], v[126:129]
	v_mfma_f32_16x16x32_bf16 v[122:125], v[86:89], v[224:227], v[122:125]
	v_mfma_f32_16x16x32_bf16 v[110:113], v[70:73], v[232:235], v[110:113]
	v_mfma_f32_16x16x32_bf16 v[106:109], v[86:89], v[232:235], v[106:109]
	v_mfma_f32_16x16x32_bf16 v[94:97], v[70:73], v[240:243], v[94:97]
	v_mfma_f32_16x16x32_bf16 v[90:93], v[86:89], v[240:243], v[90:93]
	s_setprio 0
	s_setprio 1
	v_mfma_f32_16x16x32_bf16 v[134:137], v[146:149], v[180:183], v[134:137]
	v_mfma_f32_16x16x32_bf16 v[130:133], v[168:171], v[180:183], v[130:133]
	v_mfma_f32_16x16x32_bf16 v[118:121], v[146:149], v[216:219], v[118:121]
	v_mfma_f32_16x16x32_bf16 v[114:117], v[168:171], v[216:219], v[114:117]
	v_mfma_f32_16x16x32_bf16 v[102:105], v[146:149], v[228:231], v[102:105]
	v_mfma_f32_16x16x32_bf16 v[98:101], v[168:171], v[228:231], v[98:101]
	v_mfma_f32_16x16x32_bf16 v[78:81], v[146:149], v[236:239], v[78:81]
	v_mfma_f32_16x16x32_bf16 v[74:77], v[168:171], v[236:239], v[74:77]
	v_mfma_f32_16x16x32_bf16 v[134:137], v[162:165], v[184:187], v[134:137]
	v_mfma_f32_16x16x32_bf16 v[130:133], v[176:179], v[184:187], v[130:133]
	v_mfma_f32_16x16x32_bf16 v[118:121], v[162:165], v[224:227], v[118:121]
	v_mfma_f32_16x16x32_bf16 v[114:117], v[176:179], v[224:227], v[114:117]
	v_mfma_f32_16x16x32_bf16 v[102:105], v[162:165], v[232:235], v[102:105]
	v_mfma_f32_16x16x32_bf16 v[98:101], v[176:179], v[232:235], v[98:101]
	v_mfma_f32_16x16x32_bf16 v[78:81], v[162:165], v[240:243], v[78:81]
	v_mfma_f32_16x16x32_bf16 v[74:77], v[176:179], v[240:243], v[74:77]
	s_setprio 0
	s_barrier
	s_add_i32 s10, s10, s94
	v_lshl_add_u64 v[188:189], v[188:189], 0, s[56:57]
	s_mov_b32 m0, s10
	global_load_lds_dwordx4 v[188:189], off
	v_lshl_add_u64 v[188:189], v[244:245], 0, s[56:57]
	s_add_i32 m0, s10, 0x2000
	s_add_i32 s10, s52, s94
	global_load_lds_dwordx4 v[188:189], off
	v_lshl_add_u64 v[188:189], v[246:247], 0, s[56:57]
	s_mov_b32 m0, s10
	s_nop 0
	global_load_lds_dwordx4 v[188:189], off
	v_lshl_add_u64 v[188:189], v[248:249], 0, s[56:57]
	s_add_i32 m0, s10, 0x2000
	s_nop 0
	global_load_lds_dwordx4 v[188:189], off
	v_lshl_add_u64 v[188:189], v[202:203], 0, s[56:57]
	s_mov_b32 m0, s13
	s_nop 0
	global_load_lds_dwordx4 v[188:189], off
	v_lshl_add_u64 v[188:189], v[212:213], 0, s[56:57]
	s_mov_b32 m0, s46
	s_nop 0
	global_load_lds_dwordx4 v[188:189], off
	s_waitcnt vmcnt(8)
	s_waitcnt lgkmcnt(0)
	s_barrier
	s_setprio 1
	s_waitcnt lgkmcnt(0)
	s_nop 0
	s_setprio 0
	s_setprio 1
	s_setprio 0
	s_barrier
	s_add_u32 s0, s0, 0x100
	s_addc_u32 s1, s1, 0
	s_add_u32 s44, s44, 0x100
	s_addc_u32 s45, s45, 0
	s_cmp_ge_i32 s49, s20
	s_mov_b32 s42, s49
	s_cbranch_scc0 .Lhalf_A
	s_branch .Lpost_A

.LBB0_548:
	s_add_i32 m0, s7, 0x18000
	v_lshl_add_u64 v[0:1], v[0:1], 0, s[56:57]
	s_waitcnt vmcnt(2)
	s_barrier
	global_load_lds_dwordx4 v[0:1], off
	v_lshl_add_u64 v[0:1], v[2:3], 0, s[56:57]
	s_add_i32 m0, s7, 0x1a000
	s_add_i32 s13, s7, 0x8000
	global_load_lds_dwordx4 v[0:1], off
	v_lshl_add_u64 v[0:1], v[8:9], 0, s[56:57]
	s_mov_b32 m0, s13
	s_add_i32 s46, s7, 0xa000
	global_load_lds_dwordx4 v[0:1], off
	v_lshl_add_u64 v[0:1], v[10:11], 0, s[56:57]
	s_mov_b32 m0, s46
	s_lshr_b32 s12, s29, 26
	global_load_lds_dwordx4 v[0:1], off
	s_add_i32 m0, s7, 0x1c000
	v_lshl_add_u64 v[0:1], v[4:5], 0, s[56:57]
	global_load_lds_dwordx4 v[0:1], off
	v_lshl_add_u64 v[0:1], v[6:7], 0, s[56:57]
	s_add_i32 m0, s7, 0x1e000
	v_and_b32_e32 v157, 15, v12
	global_load_lds_dwordx4 v[0:1], off
	v_bfe_u32 v0, v12, 4, 2
	s_add_i32 s12, s28, s12
	v_lshlrev_b32_e32 v1, 4, v0
	v_lshlrev_b32_e32 v2, 2, v12
	s_ashr_i32 s20, s12, 6
	s_lshl_b32 s12, s9, 6
	v_lshl_or_b32 v1, v157, 6, v1
	s_lshl_b32 s9, s9, 13
	v_and_b32_e32 v2, 32, v2
	v_bitop3_b32 v3, v1, s9, v2 bitop3:0xde
	s_lshl_b32 s9, s21, 5
	s_and_b32 s9, s9, 0x60
	s_lshl_b32 s21, s9, 7
	s_mov_b32 s10, s28
	v_writelane_b32 v255, s10, 29
	s_cmp_gt_i32 s28, 63
	s_cselect_b64 s[80:81], -1, 0
	v_writelane_b32 v255, s11, 30
	s_add_i32 s47, s20, -2
	s_cmpk_lt_u32 s6, 0x100
	v_readlane_b32 s28, v255, 27
	v_bitop3_b32 v172, v1, s21, v2 bitop3:0xde
	s_cselect_b64 s[82:83], -1, 0
	s_lshr_b32 s21, s60, 3
	s_lshl_b32 s58, s40, 3
	v_readlane_b32 s29, v255, 28
	s_cmp_lg_u64 s[28:29], 0
	v_readlane_b32 s6, v255, 32
	s_cselect_b64 s[84:85], -1, 0
	s_cmp_lg_u32 s6, 0
	v_readlane_b32 s6, v255, 31
	s_cselect_b64 s[86:87], -1, 0
	s_cmp_lg_u32 s6, 0
	v_readlane_b32 s6, v255, 20
	s_cselect_b64 s[88:89], -1, 0
	s_cmp_lg_u32 s6, 0
	s_cselect_b64 s[90:91], -1, 0
	s_abs_i32 s59, s58
	v_cvt_f32_u32_e32 v1, s59
	v_lshl_or_b32 v156, v0, 3, s9
	s_sub_i32 s6, 0, s59
	s_waitcnt vmcnt(6)
	v_rcp_iflag_f32_e32 v0, v1
	v_mov_b32_e32 v1, v33
	v_and_b32_e32 v173, 63, v12
	s_mov_b32 s61, s95
	v_mul_f32_e32 v0, 0x4f7ffffe, v0
	v_cvt_u32_f32_e32 v0, v0
	s_mov_b32 s9, 0
	v_cmp_eq_u32_e64 s[38:39], 0, v214
	v_writelane_b32 v255, s40, 54
	v_readfirstlane_b32 s28, v0
	v_add_u32_e32 v0, v15, v13
	v_add_lshl_u32 v0, v0, v14, 1
	s_mul_i32 s6, s6, s28
	v_lshl_add_u64 v[158:159], s[96:97], 0, v[0:1]
	v_add_u32_e32 v0, v18, v16
	s_mul_hi_u32 s6, s28, s6
	v_add_lshl_u32 v0, v0, v17, 1
	s_bfe_i32 s54, s40, 0x1001c
	s_add_i32 s55, s28, s6
	v_lshl_add_u64 v[160:161], s[96:97], 0, v[0:1]
	v_add_u32_e32 v174, 0, v3
	s_barrier
	s_mov_b32 s99, 0
	s_mov_b32 s98, 0
	v_readlane_b32 s28, v255, 14
	v_readlane_b32 s29, v255, 49
	s_nop 1
	s_cmpk_eq_u32 s28, 0x100
	s_cbranch_scc0 .Lha_init_done
	s_cmpk_eq_u32 s60, 0x480
	s_cbranch_scc0 .Lha_init_done
	s_mov_b32 s28, 0x8004
	s_bitcmp1_b32 s28, s29
	s_cbranch_scc0 .Lha_init_done
	v_readlane_b32 s28, v255, 8
	s_nop 1
	s_lshr_b32 s28, s28, 7
	s_and_b32 s28, s28, 1
	s_lshl_b32 s28, s28, 1
	s_or_b32 s98, s28, 1
.Lha_init_done:
	s_branch .LBB0_551
.LBB0_549:
	s_mov_b64 s[0:1], 0
.LBB0_550:
	s_andn2_b64 vcc, exec, s[0:1]
	s_cmp_eq_u32 s9, 4
	s_cselect_b32 s99, 1, 0
	s_and_b32 s99, s99, s98
	s_and_b32 s99, s99, 1
	s_mov_b32 s30, s6
	s_mov_b32 s31, s48
	s_mov_b64 s[44:45], s[28:29]
	s_mov_b64 s[0:1], s[34:35]
	s_cbranch_vccz .LBB0_758
.LBB0_551:
	s_add_i32 s9, s9, 1
	v_readlane_b32 s10, v255, 15
	s_mul_i32 s28, s9, s10
	v_readlane_b32 s10, v255, 14
	s_mul_hi_u32 s29, s9, s10
	s_add_i32 s29, s29, s28
	s_mul_i32 s28, s9, s10
	v_readlane_b32 s34, v255, 8
	v_readlane_b32 s35, v255, 9
	s_add_u32 s28, s28, s34
	s_addc_u32 s29, s29, s35
	s_bitcmp1_b32 s98, 0
	s_cbranch_scc0 .Lha_noov
	s_cmp_eq_u32 s9, 4
	s_cbranch_scc0 .Lha_noov
	s_and_b32 s28, s34, 0x7f
	s_addk_i32 s28, 0x400
	s_mov_b32 s29, 0
.Lha_noov:
	v_mov_b64_e32 v[0:1], s[60:61]
	v_cmp_ge_i64_e32 vcc, s[28:29], v[0:1]
	v_cmp_lt_i64_e64 s[42:43], s[28:29], v[0:1]
	s_cbranch_vccnz .LBB0_553
	s_ashr_i32 s6, s28, 31
	s_lshr_b32 s6, s6, 29
	s_add_i32 s6, s28, s6
	s_ashr_i32 s29, s6, 3
	s_and_b32 s6, s6, -8
	s_sub_i32 s6, s28, s6
	s_lshr_b32 s28, s6, 31
	s_add_i32 s28, s21, s28
	s_mul_i32 s6, s28, s6
	s_add_i32 s6, s6, s29
	s_abs_i32 s29, s6
	s_mul_hi_u32 s34, s29, s55
	s_mul_i32 s35, s34, s59
	s_ashr_i32 s28, s6, 31
	s_sub_i32 s29, s29, s35
	s_xor_b32 s28, s28, s54
	s_add_i32 s35, s34, 1
	s_sub_i32 s40, s29, s59
	s_cmp_ge_u32 s29, s59
	s_cselect_b32 s34, s35, s34
	s_cselect_b32 s29, s40, s29
	s_add_i32 s35, s34, 1
	s_cmp_ge_u32 s29, s59
	s_cselect_b32 s29, s35, s34
	s_xor_b32 s29, s29, s28
	s_sub_i32 s28, s29, s28
	s_lshl_b32 s29, s28, 3
	s_sub_i32 s34, s11, s29
	s_min_i32 s34, s34, 8
	s_mul_i32 s28, s28, s58
	s_sub_i32 s28, s6, s28
	s_cmp_eq_u32 s34, 8
	s_cbranch_scc0 .Lslow552
	s_lshr_b32 s6, s28, 3
	s_and_b32 s28, s28, 7
	s_add_i32 s48, s28, s29
	s_branch .LBB0_553

.LBB0_553:
	s_nop 0
	v_cndmask_b32_e64 v0, 0, 1, s[42:43]
	v_cmp_ne_u32_e64 s[40:41], 1, v0
	s_andn2_b64 vcc, exec, s[42:43]
	s_mov_b64 s[34:35], s[0:1]
	s_cbranch_vccnz .LBB0_555
	s_ashr_i32 s28, s48, 31
	s_mul_hi_u32 s29, s76, s48
	s_mul_i32 s28, s76, s28
	s_add_i32 s28, s29, s28
	s_mul_i32 s29, s77, s48
	s_add_i32 s28, s28, s29
	s_mul_i32 s29, s76, s48
	s_add_u32 s34, s24, s29
	s_addc_u32 s35, s25, s28
	s_cmp_eq_u32 s9, 4
	s_cbranch_scc0 .Lha_na
	s_and_b32 s28, s98, 3
	s_cmp_eq_u32 s28, 3
	s_cbranch_scc0 .Lha_na
	s_lshr_b64 s[28:29], s[76:77], 1
	s_add_u32 s34, s34, s28
	s_addc_u32 s35, s35, s29
.Lha_na:
.LBB0_555:
	s_and_b64 vcc, exec, s[40:41]
	s_mov_b64 s[28:29], s[44:45]
	s_cbranch_vccnz .LBB0_557
	s_ashr_i32 s28, s6, 31
	s_mul_hi_u32 s29, s76, s6
	s_mul_i32 s28, s76, s28
	s_add_i32 s28, s29, s28
	s_mul_i32 s29, s77, s6
	s_add_i32 s29, s28, s29
	s_mul_i32 s28, s76, s6
	s_add_u32 s28, s50, s28
	s_addc_u32 s29, s51, s29
.LBB0_557:
	v_mov_b32_e32 v141, 0
	s_andn2_b64 vcc, exec, s[80:81]
	v_mov_b32_e32 v140, v141
	v_mov_b32_e32 v139, v141
	v_mov_b32_e32 v138, v141
	v_mov_b32_e32 v145, v141
	v_mov_b32_e32 v144, v141
	v_mov_b32_e32 v143, v141
	v_mov_b32_e32 v142, v141
	v_mov_b32_e32 v129, v141
	v_mov_b32_e32 v128, v141
	v_mov_b32_e32 v127, v141
	v_mov_b32_e32 v126, v141
	v_mov_b32_e32 v125, v141
	v_mov_b32_e32 v124, v141
	v_mov_b32_e32 v123, v141
	v_mov_b32_e32 v122, v141
	v_mov_b32_e32 v113, v141
	v_mov_b32_e32 v112, v141
	v_mov_b32_e32 v111, v141
	v_mov_b32_e32 v110, v141
	v_mov_b32_e32 v109, v141
	v_mov_b32_e32 v108, v141
	v_mov_b32_e32 v107, v141
	v_mov_b32_e32 v106, v141
	v_mov_b32_e32 v97, v141
	v_mov_b32_e32 v96, v141
	v_mov_b32_e32 v95, v141
	v_mov_b32_e32 v94, v141
	v_mov_b32_e32 v93, v141
	v_mov_b32_e32 v92, v141
	v_mov_b32_e32 v91, v141
	v_mov_b32_e32 v90, v141
	v_mov_b32_e32 v137, v141
	v_mov_b32_e32 v136, v141
	v_mov_b32_e32 v135, v141
	v_mov_b32_e32 v134, v141
	v_mov_b32_e32 v133, v141
	v_mov_b32_e32 v132, v141
	v_mov_b32_e32 v131, v141
	v_mov_b32_e32 v130, v141
	v_mov_b32_e32 v121, v141
	v_mov_b32_e32 v120, v141
	v_mov_b32_e32 v119, v141
	v_mov_b32_e32 v118, v141
	v_mov_b32_e32 v117, v141
	v_mov_b32_e32 v116, v141
	v_mov_b32_e32 v115, v141
	v_mov_b32_e32 v114, v141
	v_mov_b32_e32 v105, v141
	v_mov_b32_e32 v104, v141
	v_mov_b32_e32 v103, v141
	v_mov_b32_e32 v102, v141
	v_mov_b32_e32 v101, v141
	v_mov_b32_e32 v100, v141
	v_mov_b32_e32 v99, v141
	v_mov_b32_e32 v98, v141
	v_mov_b32_e32 v81, v141
	v_mov_b32_e32 v80, v141
	v_mov_b32_e32 v79, v141
	v_mov_b32_e32 v78, v141
	v_mov_b32_e32 v77, v141
	v_mov_b32_e32 v76, v141
	v_mov_b32_e32 v75, v141
	v_mov_b32_e32 v74, v141
	v_mov_b32_e32 v65, v141
	v_mov_b32_e32 v64, v141
	v_mov_b32_e32 v63, v141
	v_mov_b32_e32 v62, v141
	v_mov_b32_e32 v61, v141
	v_mov_b32_e32 v60, v141
	v_mov_b32_e32 v59, v141
	v_mov_b32_e32 v58, v141
	v_mov_b32_e32 v49, v141
	v_mov_b32_e32 v48, v141
	v_mov_b32_e32 v47, v141
	v_mov_b32_e32 v46, v141
	v_mov_b32_e32 v45, v141
	v_mov_b32_e32 v44, v141
	v_mov_b32_e32 v43, v141
	v_mov_b32_e32 v42, v141
	v_mov_b32_e32 v31, v141
	v_mov_b32_e32 v30, v141
	v_mov_b32_e32 v29, v141
	v_mov_b32_e32 v28, v141
	v_mov_b32_e32 v27, v141
	v_mov_b32_e32 v26, v141
	v_mov_b32_e32 v25, v141
	v_mov_b32_e32 v24, v141
	v_mov_b32_e32 v15, v141
	v_mov_b32_e32 v14, v141
	v_mov_b32_e32 v13, v141
	v_mov_b32_e32 v12, v141
	v_mov_b32_e32 v11, v141
	v_mov_b32_e32 v10, v141
	v_mov_b32_e32 v9, v141
	v_mov_b32_e32 v8, v141
	v_mov_b32_e32 v57, v141
	v_mov_b32_e32 v56, v141
	v_mov_b32_e32 v55, v141
	v_mov_b32_e32 v54, v141
	v_mov_b32_e32 v53, v141
	v_mov_b32_e32 v52, v141
	v_mov_b32_e32 v51, v141
	v_mov_b32_e32 v50, v141
	v_mov_b32_e32 v41, v141
	v_mov_b32_e32 v40, v141
	v_mov_b32_e32 v39, v141
	v_mov_b32_e32 v38, v141
	v_mov_b32_e32 v37, v141
	v_mov_b32_e32 v36, v141
	v_mov_b32_e32 v35, v141
	v_mov_b32_e32 v34, v141
	v_mov_b32_e32 v23, v141
	v_mov_b32_e32 v22, v141
	v_mov_b32_e32 v21, v141
	v_mov_b32_e32 v20, v141
	v_mov_b32_e32 v19, v141
	v_mov_b32_e32 v18, v141
	v_mov_b32_e32 v17, v141
	v_mov_b32_e32 v16, v141
	v_mov_b32_e32 v7, v141
	v_mov_b32_e32 v6, v141
	v_mov_b32_e32 v5, v141
	v_mov_b32_e32 v4, v141
	v_mov_b32_e32 v3, v141
	v_mov_b32_e32 v2, v141
	v_mov_b32_e32 v1, v141
	v_mov_b32_e32 v0, v141
	s_cbranch_vccnz .LBB0_561
	s_add_u32 s0, s0, 0x80
	s_addc_u32 s1, s1, 0
	s_add_u32 s44, s44, 0x100
	s_addc_u32 s45, s45, 0
	s_mov_b32 s42, 0
	s_bitcmp1_b32 s99, 0
	s_cbranch_scc1 .Lhalf_A
.LBB0_559:
	s_add_i32 s49, s42, 2
	s_add_u32 vcc_lo, s0, 0x80
	s_addc_u32 s43, s1, 0
	s_add_i32 s10, 0, 0x10000
	s_cmp_eq_u32 s47, s42
	s_cselect_b32 s43, s35, s43
	s_cselect_b32 s42, s34, vcc_lo
	s_cselect_b32 vcc_hi, s29, s45
	s_cselect_b32 vcc_lo, s28, s44
	s_add_i32 s52, 0, 0x14000
	v_add_u32_e32 v86, s10, v172
	v_add_u32_e32 v175, s52, v172
	ds_read_b128 v[66:69], v86
	ds_read_b128 v[70:73], v86 offset:1024
	ds_read_b128 v[82:85], v86 offset:2048
	ds_read_b128 v[86:89], v86 offset:3072
	ds_read_b128 v[146:149], v175
	ds_read_b128 v[162:165], v175 offset:1024
	ds_read_b128 v[168:171], v175 offset:2048
	ds_read_b128 v[176:179], v175 offset:3072
	v_lshl_add_u64 v[188:189], s[0:1], 0, v[158:159]
	s_add_i32 m0, s7, 0xc000
	ds_read_b128 v[180:183], v174
	ds_read_b128 v[184:187], v174 offset:1024
	ds_read_b128 v[216:219], v174 offset:2048
	ds_read_b128 v[224:227], v174 offset:3072
	ds_read_b128 v[228:231], v174 offset:4096
	ds_read_b128 v[232:235], v174 offset:5120
	ds_read_b128 v[236:239], v174 offset:6144
	ds_read_b128 v[240:243], v174 offset:7168
	global_load_lds_dwordx4 v[188:189], off
	v_lshl_add_u64 v[188:189], s[0:1], 0, v[160:161]
	s_add_i32 m0, s7, 0xe000
	s_nop 0
	global_load_lds_dwordx4 v[188:189], off
	s_waitcnt vmcnt(8)
	s_waitcnt lgkmcnt(0)
	s_barrier
	s_setprio 1
	s_waitcnt lgkmcnt(0)
	s_nop 0
	v_mfma_f32_16x16x32_bf16 v[138:141], v[66:69], v[180:183], v[138:141]
	v_mfma_f32_16x16x32_bf16 v[142:145], v[82:85], v[180:183], v[142:145]
	v_mfma_f32_16x16x32_bf16 v[126:129], v[66:69], v[216:219], v[126:129]
	v_mfma_f32_16x16x32_bf16 v[122:125], v[82:85], v[216:219], v[122:125]
	v_mfma_f32_16x16x32_bf16 v[110:113], v[66:69], v[228:231], v[110:113]
	v_mfma_f32_16x16x32_bf16 v[106:109], v[82:85], v[228:231], v[106:109]
	v_mfma_f32_16x16x32_bf16 v[94:97], v[66:69], v[236:239], v[94:97]
	v_mfma_f32_16x16x32_bf16 v[90:93], v[82:85], v[236:239], v[90:93]
	v_mfma_f32_16x16x32_bf16 v[138:141], v[70:73], v[184:187], v[138:141]
	v_mfma_f32_16x16x32_bf16 v[142:145], v[86:89], v[184:187], v[142:145]
	v_mfma_f32_16x16x32_bf16 v[126:129], v[70:73], v[224:227], v[126:129]
	v_mfma_f32_16x16x32_bf16 v[122:125], v[86:89], v[224:227], v[122:125]
	v_mfma_f32_16x16x32_bf16 v[110:113], v[70:73], v[232:235], v[110:113]
	v_mfma_f32_16x16x32_bf16 v[106:109], v[86:89], v[232:235], v[106:109]
	v_mfma_f32_16x16x32_bf16 v[94:97], v[70:73], v[240:243], v[94:97]
	v_mfma_f32_16x16x32_bf16 v[90:93], v[86:89], v[240:243], v[90:93]
	s_setprio 0
	s_setprio 1
	v_mfma_f32_16x16x32_bf16 v[134:137], v[146:149], v[180:183], v[134:137]
	v_mfma_f32_16x16x32_bf16 v[130:133], v[168:171], v[180:183], v[130:133]
	v_mfma_f32_16x16x32_bf16 v[118:121], v[146:149], v[216:219], v[118:121]
	v_mfma_f32_16x16x32_bf16 v[114:117], v[168:171], v[216:219], v[114:117]
	v_mfma_f32_16x16x32_bf16 v[102:105], v[146:149], v[228:231], v[102:105]
	v_mfma_f32_16x16x32_bf16 v[98:101], v[168:171], v[228:231], v[98:101]
	v_mfma_f32_16x16x32_bf16 v[78:81], v[146:149], v[236:239], v[78:81]
	v_mfma_f32_16x16x32_bf16 v[74:77], v[168:171], v[236:239], v[74:77]
	v_mfma_f32_16x16x32_bf16 v[134:137], v[162:165], v[184:187], v[134:137]
	v_mfma_f32_16x16x32_bf16 v[130:133], v[176:179], v[184:187], v[130:133]
	v_mfma_f32_16x16x32_bf16 v[118:121], v[162:165], v[224:227], v[118:121]
	v_mfma_f32_16x16x32_bf16 v[114:117], v[176:179], v[224:227], v[114:117]
	v_mfma_f32_16x16x32_bf16 v[102:105], v[162:165], v[232:235], v[102:105]
	v_mfma_f32_16x16x32_bf16 v[98:101], v[176:179], v[232:235], v[98:101]
	v_mfma_f32_16x16x32_bf16 v[78:81], v[162:165], v[240:243], v[78:81]
	v_mfma_f32_16x16x32_bf16 v[74:77], v[176:179], v[240:243], v[74:77]
	s_setprio 0
	s_barrier
	s_add_i32 s10, s10, s94
	v_lshl_add_u64 v[188:189], vcc, 0, v[32:33]
	s_mov_b32 m0, s10
	ds_read_b128 v[180:183], v174 offset:16384
	ds_read_b128 v[184:187], v174 offset:17408
	ds_read_b128 v[216:219], v174 offset:18432
	ds_read_b128 v[224:227], v174 offset:19456
	ds_read_b128 v[228:231], v174 offset:20480
	ds_read_b128 v[232:235], v174 offset:21504
	ds_read_b128 v[236:239], v174 offset:22528
	ds_read_b128 v[240:243], v174 offset:23552
	global_load_lds_dwordx4 v[188:189], off
	s_add_i32 m0, s10, 0x2000
	v_lshl_add_u64 v[244:245], vcc, 0, v[154:155]
	s_add_u32 vcc_lo, vcc_lo, s96
	s_addc_u32 vcc_hi, vcc_hi, s97
	s_add_i32 s10, s52, s94
	global_load_lds_dwordx4 v[244:245], off
	v_lshl_add_u64 v[246:247], vcc, 0, v[32:33]
	s_mov_b32 m0, s10
	v_lshl_add_u64 v[248:249], vcc, 0, v[154:155]
	global_load_lds_dwordx4 v[246:247], off
	s_add_i32 m0, s10, 0x2000
	v_lshl_add_u64 v[202:203], s[42:43], 0, v[150:151]
	global_load_lds_dwordx4 v[248:249], off
	s_mov_b32 m0, s7
	v_lshl_add_u64 v[212:213], s[42:43], 0, v[152:153]
	global_load_lds_dwordx4 v[202:203], off
	s_mov_b32 m0, s2
	s_nop 0
	global_load_lds_dwordx4 v[212:213], off
	s_waitcnt vmcnt(8)
	s_waitcnt lgkmcnt(0)
	s_barrier
	s_setprio 1
	s_waitcnt lgkmcnt(0)
	v_mfma_f32_16x16x32_bf16 v[62:65], v[66:69], v[180:183], v[62:65]
	v_mfma_f32_16x16x32_bf16 v[58:61], v[82:85], v[180:183], v[58:61]
	v_mfma_f32_16x16x32_bf16 v[46:49], v[66:69], v[216:219], v[46:49]
	v_mfma_f32_16x16x32_bf16 v[42:45], v[82:85], v[216:219], v[42:45]
	v_mfma_f32_16x16x32_bf16 v[28:31], v[66:69], v[228:231], v[28:31]
	v_mfma_f32_16x16x32_bf16 v[24:27], v[82:85], v[228:231], v[24:27]
	v_mfma_f32_16x16x32_bf16 v[12:15], v[66:69], v[236:239], v[12:15]
	v_mfma_f32_16x16x32_bf16 v[8:11], v[82:85], v[236:239], v[8:11]
	v_mfma_f32_16x16x32_bf16 v[62:65], v[70:73], v[184:187], v[62:65]
	v_mfma_f32_16x16x32_bf16 v[58:61], v[86:89], v[184:187], v[58:61]
	v_mfma_f32_16x16x32_bf16 v[46:49], v[70:73], v[224:227], v[46:49]
	v_mfma_f32_16x16x32_bf16 v[42:45], v[86:89], v[224:227], v[42:45]
	v_mfma_f32_16x16x32_bf16 v[28:31], v[70:73], v[232:235], v[28:31]
	v_mfma_f32_16x16x32_bf16 v[24:27], v[86:89], v[232:235], v[24:27]
	v_mfma_f32_16x16x32_bf16 v[12:15], v[70:73], v[240:243], v[12:15]
	v_mfma_f32_16x16x32_bf16 v[8:11], v[86:89], v[240:243], v[8:11]
	s_setprio 0
	s_setprio 1
	v_mfma_f32_16x16x32_bf16 v[54:57], v[146:149], v[180:183], v[54:57]
	v_mfma_f32_16x16x32_bf16 v[50:53], v[168:171], v[180:183], v[50:53]
	v_mfma_f32_16x16x32_bf16 v[38:41], v[146:149], v[216:219], v[38:41]
	v_mfma_f32_16x16x32_bf16 v[34:37], v[168:171], v[216:219], v[34:37]
	v_mfma_f32_16x16x32_bf16 v[20:23], v[146:149], v[228:231], v[20:23]
	v_mfma_f32_16x16x32_bf16 v[16:19], v[168:171], v[228:231], v[16:19]
	v_mfma_f32_16x16x32_bf16 v[4:7], v[146:149], v[236:239], v[4:7]
	v_mfma_f32_16x16x32_bf16 v[0:3], v[168:171], v[236:239], v[0:3]
	v_mfma_f32_16x16x32_bf16 v[54:57], v[162:165], v[184:187], v[54:57]
	v_mfma_f32_16x16x32_bf16 v[50:53], v[176:179], v[184:187], v[50:53]
	v_mfma_f32_16x16x32_bf16 v[38:41], v[162:165], v[224:227], v[38:41]
	v_mfma_f32_16x16x32_bf16 v[34:37], v[176:179], v[224:227], v[34:37]
	v_mfma_f32_16x16x32_bf16 v[20:23], v[162:165], v[232:235], v[20:23]
	v_mfma_f32_16x16x32_bf16 v[16:19], v[176:179], v[232:235], v[16:19]
	v_mfma_f32_16x16x32_bf16 v[4:7], v[162:165], v[240:243], v[4:7]
	v_mfma_f32_16x16x32_bf16 v[0:3], v[176:179], v[240:243], v[0:3]
	s_setprio 0
	s_barrier
	s_add_i32 s10, 0, 0x18000
	s_add_i32 s52, 0, 0x1c000
	v_add_u32_e32 v86, s10, v172
	v_add_u32_e32 v175, s52, v172
	ds_read_b128 v[66:69], v86
	ds_read_b128 v[70:73], v86 offset:1024
	ds_read_b128 v[82:85], v86 offset:2048
	ds_read_b128 v[86:89], v86 offset:3072
	ds_read_b128 v[146:149], v175
	ds_read_b128 v[162:165], v175 offset:1024
	ds_read_b128 v[168:171], v175 offset:2048
	ds_read_b128 v[176:179], v175 offset:3072
	s_add_u32 s42, s42, s96
	s_addc_u32 s43, s43, s97
	s_mov_b32 m0, s3
	v_lshl_add_u64 v[204:205], s[42:43], 0, v[150:151]
	ds_read_b128 v[180:183], v174 offset:32768
	ds_read_b128 v[184:187], v174 offset:33792
	ds_read_b128 v[216:219], v174 offset:34816
	ds_read_b128 v[224:227], v174 offset:35840
	ds_read_b128 v[228:231], v174 offset:36864
	ds_read_b128 v[232:235], v174 offset:37888
	ds_read_b128 v[236:239], v174 offset:38912
	ds_read_b128 v[240:243], v174 offset:39936
	global_load_lds_dwordx4 v[204:205], off
	v_lshl_add_u64 v[204:205], s[42:43], 0, v[152:153]
	s_mov_b32 m0, s17
	s_nop 0
	global_load_lds_dwordx4 v[204:205], off
	s_waitcnt vmcnt(8)
	s_waitcnt lgkmcnt(0)
	s_barrier
	s_setprio 1
	s_waitcnt lgkmcnt(0)
	v_mfma_f32_16x16x32_bf16 v[138:141], v[66:69], v[180:183], v[138:141]
	v_mfma_f32_16x16x32_bf16 v[142:145], v[82:85], v[180:183], v[142:145]
	v_mfma_f32_16x16x32_bf16 v[126:129], v[66:69], v[216:219], v[126:129]
	v_mfma_f32_16x16x32_bf16 v[122:125], v[82:85], v[216:219], v[122:125]
	v_mfma_f32_16x16x32_bf16 v[110:113], v[66:69], v[228:231], v[110:113]
	v_mfma_f32_16x16x32_bf16 v[106:109], v[82:85], v[228:231], v[106:109]
	v_mfma_f32_16x16x32_bf16 v[94:97], v[66:69], v[236:239], v[94:97]
	v_mfma_f32_16x16x32_bf16 v[90:93], v[82:85], v[236:239], v[90:93]
	v_mfma_f32_16x16x32_bf16 v[138:141], v[70:73], v[184:187], v[138:141]
	v_mfma_f32_16x16x32_bf16 v[142:145], v[86:89], v[184:187], v[142:145]
	v_mfma_f32_16x16x32_bf16 v[126:129], v[70:73], v[224:227], v[126:129]
	v_mfma_f32_16x16x32_bf16 v[122:125], v[86:89], v[224:227], v[122:125]
	v_mfma_f32_16x16x32_bf16 v[110:113], v[70:73], v[232:235], v[110:113]
	v_mfma_f32_16x16x32_bf16 v[106:109], v[86:89], v[232:235], v[106:109]
	v_mfma_f32_16x16x32_bf16 v[94:97], v[70:73], v[240:243], v[94:97]
	v_mfma_f32_16x16x32_bf16 v[90:93], v[86:89], v[240:243], v[90:93]
	s_setprio 0
	s_setprio 1
	v_mfma_f32_16x16x32_bf16 v[134:137], v[146:149], v[180:183], v[134:137]
	v_mfma_f32_16x16x32_bf16 v[130:133], v[168:171], v[180:183], v[130:133]
	v_mfma_f32_16x16x32_bf16 v[118:121], v[146:149], v[216:219], v[118:121]
	v_mfma_f32_16x16x32_bf16 v[114:117], v[168:171], v[216:219], v[114:117]
	v_mfma_f32_16x16x32_bf16 v[102:105], v[146:149], v[228:231], v[102:105]
	v_mfma_f32_16x16x32_bf16 v[98:101], v[168:171], v[228:231], v[98:101]
	v_mfma_f32_16x16x32_bf16 v[78:81], v[146:149], v[236:239], v[78:81]
	v_mfma_f32_16x16x32_bf16 v[74:77], v[168:171], v[236:239], v[74:77]
	v_mfma_f32_16x16x32_bf16 v[134:137], v[162:165], v[184:187], v[134:137]
	v_mfma_f32_16x16x32_bf16 v[130:133], v[176:179], v[184:187], v[130:133]
	v_mfma_f32_16x16x32_bf16 v[118:121], v[162:165], v[224:227], v[118:121]
	v_mfma_f32_16x16x32_bf16 v[114:117], v[176:179], v[224:227], v[114:117]
	v_mfma_f32_16x16x32_bf16 v[102:105], v[162:165], v[232:235], v[102:105]
	v_mfma_f32_16x16x32_bf16 v[98:101], v[176:179], v[232:235], v[98:101]
	v_mfma_f32_16x16x32_bf16 v[78:81], v[162:165], v[240:243], v[78:81]
	v_mfma_f32_16x16x32_bf16 v[74:77], v[176:179], v[240:243], v[74:77]
	s_setprio 0
	s_barrier
	s_add_i32 s10, s10, s94
	v_lshl_add_u64 v[188:189], v[188:189], 0, s[56:57]
	s_mov_b32 m0, s10
	ds_read_b128 v[180:183], v174 offset:49152
	ds_read_b128 v[184:187], v174 offset:50176
	ds_read_b128 v[216:219], v174 offset:51200
	ds_read_b128 v[224:227], v174 offset:52224
	ds_read_b128 v[228:231], v174 offset:53248
	ds_read_b128 v[232:235], v174 offset:54272
	ds_read_b128 v[236:239], v174 offset:55296
	ds_read_b128 v[240:243], v174 offset:56320
	global_load_lds_dwordx4 v[188:189], off
	v_lshl_add_u64 v[188:189], v[244:245], 0, s[56:57]
	s_add_i32 m0, s10, 0x2000
	s_add_i32 s10, s52, s94
	global_load_lds_dwordx4 v[188:189], off
	v_lshl_add_u64 v[188:189], v[246:247], 0, s[56:57]
	s_mov_b32 m0, s10
	s_nop 0
	global_load_lds_dwordx4 v[188:189], off
	v_lshl_add_u64 v[188:189], v[248:249], 0, s[56:57]
	s_add_i32 m0, s10, 0x2000
	s_nop 0
	global_load_lds_dwordx4 v[188:189], off
	v_lshl_add_u64 v[188:189], v[202:203], 0, s[56:57]
	s_mov_b32 m0, s13
	s_nop 0
	global_load_lds_dwordx4 v[188:189], off
	v_lshl_add_u64 v[188:189], v[212:213], 0, s[56:57]
	s_mov_b32 m0, s46
	s_nop 0
	global_load_lds_dwordx4 v[188:189], off
	s_waitcnt vmcnt(8)
	s_waitcnt lgkmcnt(0)
	s_barrier
	s_setprio 1
	s_waitcnt lgkmcnt(0)
	s_nop 0
	v_mfma_f32_16x16x32_bf16 v[62:65], v[66:69], v[180:183], v[62:65]
	v_mfma_f32_16x16x32_bf16 v[58:61], v[82:85], v[180:183], v[58:61]
	v_mfma_f32_16x16x32_bf16 v[46:49], v[66:69], v[216:219], v[46:49]
	v_mfma_f32_16x16x32_bf16 v[42:45], v[82:85], v[216:219], v[42:45]
	v_mfma_f32_16x16x32_bf16 v[28:31], v[66:69], v[228:231], v[28:31]
	v_mfma_f32_16x16x32_bf16 v[24:27], v[82:85], v[228:231], v[24:27]
	v_mfma_f32_16x16x32_bf16 v[12:15], v[66:69], v[236:239], v[12:15]
	v_mfma_f32_16x16x32_bf16 v[8:11], v[82:85], v[236:239], v[8:11]
	v_mfma_f32_16x16x32_bf16 v[62:65], v[70:73], v[184:187], v[62:65]
	v_mfma_f32_16x16x32_bf16 v[58:61], v[86:89], v[184:187], v[58:61]
	v_mfma_f32_16x16x32_bf16 v[46:49], v[70:73], v[224:227], v[46:49]
	v_mfma_f32_16x16x32_bf16 v[42:45], v[86:89], v[224:227], v[42:45]
	v_mfma_f32_16x16x32_bf16 v[28:31], v[70:73], v[232:235], v[28:31]
	v_mfma_f32_16x16x32_bf16 v[24:27], v[86:89], v[232:235], v[24:27]
	v_mfma_f32_16x16x32_bf16 v[12:15], v[70:73], v[240:243], v[12:15]
	v_mfma_f32_16x16x32_bf16 v[8:11], v[86:89], v[240:243], v[8:11]
	s_setprio 0
	s_setprio 1
	v_mfma_f32_16x16x32_bf16 v[54:57], v[146:149], v[180:183], v[54:57]
	v_mfma_f32_16x16x32_bf16 v[50:53], v[168:171], v[180:183], v[50:53]
	v_mfma_f32_16x16x32_bf16 v[38:41], v[146:149], v[216:219], v[38:41]
	v_mfma_f32_16x16x32_bf16 v[34:37], v[168:171], v[216:219], v[34:37]
	v_mfma_f32_16x16x32_bf16 v[20:23], v[146:149], v[228:231], v[20:23]
	v_mfma_f32_16x16x32_bf16 v[16:19], v[168:171], v[228:231], v[16:19]
	v_mfma_f32_16x16x32_bf16 v[4:7], v[146:149], v[236:239], v[4:7]
	v_mfma_f32_16x16x32_bf16 v[0:3], v[168:171], v[236:239], v[0:3]
	v_mfma_f32_16x16x32_bf16 v[54:57], v[162:165], v[184:187], v[54:57]
	v_mfma_f32_16x16x32_bf16 v[50:53], v[176:179], v[184:187], v[50:53]
	v_mfma_f32_16x16x32_bf16 v[38:41], v[162:165], v[224:227], v[38:41]
	v_mfma_f32_16x16x32_bf16 v[34:37], v[176:179], v[224:227], v[34:37]
	v_mfma_f32_16x16x32_bf16 v[20:23], v[162:165], v[232:235], v[20:23]
	v_mfma_f32_16x16x32_bf16 v[16:19], v[176:179], v[232:235], v[16:19]
	v_mfma_f32_16x16x32_bf16 v[4:7], v[162:165], v[240:243], v[4:7]
	v_mfma_f32_16x16x32_bf16 v[0:3], v[176:179], v[240:243], v[0:3]
	s_setprio 0
	s_barrier
	s_add_u32 s0, s0, 0x100
	s_addc_u32 s1, s1, 0
	s_add_u32 s44, s44, 0x100
	s_addc_u32 s45, s45, 0
	s_cmp_ge_i32 s49, s20
	s_mov_b32 s42, s49
	s_cbranch_scc0 .LBB0_559
.Lpost_A:
	v_readlane_b32 s52, v252, 10
	v_readlane_b32 s53, v252, 11

.LBB0_571:
	s_lshl_b32 s31, s31, 8
	s_andn2_b64 vcc, exec, s[86:87]
	s_add_i32 s31, s31, s12
	s_lshl_b32 s0, s98, 6
	s_and_b32 s0, s0, 0x80
	s_bitcmp1_b32 s99, 0
	s_cselect_b32 s0, s0, 0
	s_add_i32 s31, s31, s0
	s_cbranch_vccnz .LBB0_573
	v_or_b32_e32 v146, s31, v173
	v_ashrrev_i32_e32 v147, 31, v146
	v_lshlrev_b64 v[146:147], 6, v[146:147]
	v_lshl_add_u64 v[164:165], s[52:53], 0, v[146:147]
	s_mov_b64 s[0:1], 0x2000
	v_lshl_add_u64 v[188:189], v[164:165], 0, s[0:1]
	global_load_dwordx4 v[146:149], v[164:165], off offset:32
	global_load_dwordx4 v[168:171], v[164:165], off offset:48
	global_load_dwordx4 v[176:179], v[164:165], off
	global_load_dwordx4 v[180:183], v[164:165], off offset:16
	v_add_co_u32_e32 v164, vcc, 0x2000, v164
	s_mov_b32 s0, 0x3a800000
	s_nop 0
	v_addc_co_u32_e32 v165, vcc, 0, v165, vcc
	global_load_dwordx4 v[184:187], v[164:165], off
	global_load_dwordx4 v[216:219], v[188:189], off offset:16
	global_load_dwordx4 v[224:227], v[188:189], off offset:32
	global_load_dwordx4 v[228:231], v[188:189], off offset:48
	s_mov_b32 s42, 0x45800000
	s_waitcnt vmcnt(0)
	v_pk_add_f32 v[148:149], v[148:149], v[170:171]
	v_pk_add_f32 v[146:147], v[146:147], v[168:169]
	v_pk_add_f32 v[164:165], v[178:179], v[182:183]
	v_pk_add_f32 v[176:177], v[176:177], v[180:181]
	v_pk_add_f32 v[148:149], v[164:165], v[148:149]
	v_pk_add_f32 v[146:147], v[176:177], v[146:147]
	v_pk_add_f32 v[164:165], v[186:187], v[218:219]
	v_pk_add_f32 v[168:169], v[184:185], v[216:217]
	v_pk_add_f32 v[170:171], v[226:227], v[230:231]
	v_pk_add_f32 v[176:177], v[224:225], v[228:229]
	v_pk_add_f32 v[164:165], v[164:165], v[170:171]
	v_pk_add_f32 v[168:169], v[168:169], v[176:177]
	v_mov_b32_e32 v178, v146
	v_mov_b32_e32 v146, v148
	v_mov_b32_e32 v179, v168
	v_mov_b32_e32 v168, v147
	v_mov_b32_e32 v147, v164
	v_mov_b32_e32 v164, v149
	v_pk_add_f32 v[148:149], v[178:179], v[168:169]
	v_pk_add_f32 v[146:147], v[146:147], v[164:165]
	s_nop 0
	v_pk_add_f32 v[146:147], v[148:149], v[146:147]
	s_nop 0
	v_pk_fma_f32 v[146:147], v[146:147], s[0:1], v[166:167] op_sel_hi:[1,0,0]
	s_mov_b32 s0, 0x800000
	v_mul_f32_e32 v148, 0x4b800000, v146
	v_mul_f32_e32 v149, 0x4b800000, v147
	v_cmp_gt_f32_e32 vcc, s0, v146
	v_cmp_gt_f32_e64 s[0:1], s0, v147
	s_nop 0
	v_cndmask_b32_e32 v146, v146, v148, vcc
	v_cndmask_b32_e64 v147, v147, v149, s[0:1]
	v_rsq_f32_e32 v146, v146
	v_rsq_f32_e32 v147, v147
	s_nop 0
	v_pk_mul_f32 v[148:149], v[146:147], s[42:43] op_sel_hi:[1,0]
	s_nop 0
	v_cndmask_b32_e32 v176, v146, v148, vcc
	v_cndmask_b32_e64 v163, v147, v149, s[0:1]
	s_branch .LBB0_574

.LBB0_614:
	s_bitcmp1_b32 s99, 0
	s_cbranch_scc1 .LBB0_654
	ds_bpermute_b32 v74, v175, v163
	s_and_b64 vcc, exec, s[42:43]
	s_waitcnt lgkmcnt(0)
	v_pk_fma_f32 v[64:65], v[64:65], v[74:75], v[88:89] op_sel_hi:[1,0,1]
	v_pk_fma_f32 v[62:63], v[62:63], v[74:75], v[86:87] op_sel_hi:[1,0,1]
	v_pk_fma_f32 v[60:61], v[60:61], v[74:75], v[84:85] op_sel_hi:[1,0,1]
	v_pk_fma_f32 v[58:59], v[58:59], v[74:75], v[82:83] op_sel_hi:[1,0,1]
	s_cbranch_vccnz .LBB0_616
	v_max_f32_e32 v62, 0, v62
	v_max_f32_e32 v58, 0, v58
	v_max_f32_e32 v63, 0, v63
	v_max_f32_e32 v59, 0, v59
	v_max_f32_e32 v64, 0, v64
	v_max_f32_e32 v60, 0, v60
	v_max_f32_e32 v65, 0, v65
	v_max_f32_e32 v61, 0, v61
	v_pk_mul_f32 v[62:63], v[62:63], v[62:63]
	v_pk_mul_f32 v[64:65], v[64:65], v[64:65]
	v_pk_mul_f32 v[58:59], v[58:59], v[58:59]
	v_pk_mul_f32 v[60:61], v[60:61], v[60:61]
